# flash unit queue split into eight per-XCD queues (four batch-head pairs each, so concurrent units on one XCD share K/V through its L2), with stealing once the own queue is empty
# speedup vs baseline: 1.0074x; 1.0074x over previous
.LBB0_1936:
	s_cmp_lt_u32 s87, 64
	s_cselect_b64 s[8:9], -1, 0
	s_add_u32 s74, s20, 0x47000000
	s_addc_u32 s76, s21, 0
	s_add_u32 s71, s20, 0x48100000
	s_addc_u32 s72, s21, 0
	s_add_u32 s39, s20, 0x49200000
	v_mbcnt_lo_u32_b32 v0, -1, 0
	v_mbcnt_hi_u32_b32 v0, -1, v0
	s_addc_u32 s70, s21, 0
	v_add_u32_e32 v203, s37, v0
	s_cmp_lg_u32 0, -1
	v_bfe_u32 v3, v203, 5, 1
	s_waitcnt lgkmcnt(5)
	v_lshlrev_b32_e32 v4, 1, v203
	s_cselect_b32 s0, 0, 0
	v_lshlrev_b32_e32 v209, 2, v3
	v_lshrrev_b32_e32 v7, 2, v203
	v_and_b32_e32 v1, 63, v203
	v_and_b32_e32 v208, 31, v203
	v_lshlrev_b32_e32 v5, 3, v203
	v_and_b32_e32 v4, 32, v4
	s_addk_i32 s0, 0x6000
	v_and_or_b32 v7, v7, 3, v209
	v_lshlrev_b32_e32 v0, 10, v1
	v_and_b32_e32 v2, 24, v5
	v_add_u32_e32 v6, s0, v4
	v_lshlrev_b32_e32 v7, 6, v7
	v_lshlrev_b32_e32 v8, 10, v3
	v_lshlrev_b32_e32 v9, 4, v208
	v_add_u32_e32 v10, 0, v4
	v_cmp_gt_u32_e64 s[4:5], 32, v1
	v_bfe_u32 v1, v203, 3, 3
	v_lshlrev_b32_e32 v4, 10, v208
	v_add3_u32 v210, v10, v2, v7
	v_add3_u32 v211, v6, v2, v7
	v_add3_u32 v212, 0, v8, v9
	v_and_b32_e32 v6, 56, v5
	v_or_b32_e32 v5, 8, v1
	v_or_b32_e32 v7, 16, v1
	v_or_b32_e32 v9, 24, v1
	v_lshl_or_b32 v4, v3, 3, v4
	v_or_b32_e32 v11, 2, v209
	v_or_b32_e32 v13, 3, v209
	v_or_b32_e32 v15, 8, v209
	v_or_b32_e32 v16, 9, v209
	v_or_b32_e32 v17, 10, v209
	v_or_b32_e32 v18, 11, v209
	v_or_b32_e32 v19, 16, v209
	v_or_b32_e32 v20, 17, v209
	v_or_b32_e32 v221, 18, v209
	v_or_b32_e32 v222, 19, v209
	v_or_b32_e32 v223, 24, v209
	v_or_b32_e32 v224, 25, v209
	v_or_b32_e32 v225, 26, v209
	v_or_b32_e32 v226, 27, v209
	v_lshlrev_b32_e32 v8, 10, v1
	v_lshlrev_b32_e32 v10, 10, v5
	v_lshlrev_b32_e32 v12, 10, v7
	v_lshlrev_b32_e32 v14, 10, v9
	v_lshlrev_b32_e32 v239, 9, v3
	s_mov_b32 s14, 2.0
	s_mov_b32 s16, 0x41000000
	s_mov_b32 s24, 0x41200000
	s_mov_b32 s26, 0x41800000
	s_mov_b32 s28, 0x41900000
	s_mov_b32 s30, 0x41c00000
	s_mov_b32 s34, 0x41d00000
	s_mov_b32 s56, 0xfffe0000
	v_mov_b32_e32 v189, 0
	s_mov_b32 s11, 0
	v_or_b32_e32 v227, 0xc0, v209
	v_or_b32_e32 v228, 0xf2, v209
	v_or_b32_e32 v229, 0xd3, v209
	v_or_b32_e32 v230, 0xf3, v209
	v_or_b32_e32 v231, 0xd8, v209
	v_or_b32_e32 v232, 0xf8, v209
	v_or_b32_e32 v233, 0xd9, v209
	v_or_b32_e32 v234, 0xf9, v209
	v_or_b32_e32 v235, 0xda, v209
	v_or_b32_e32 v236, 0xfa, v209
	v_or_b32_e32 v237, 0xdb, v209
	v_or_b32_e32 v238, 0xfb, v209
	v_or_b32_e32 v240, 0x80, v239
	v_lshlrev_b32_e32 v241, 7, v11
	v_lshlrev_b32_e32 v242, 7, v13
	v_lshlrev_b32_e32 v243, 7, v15
	v_lshlrev_b32_e32 v244, 7, v16
	v_lshlrev_b32_e32 v245, 7, v17
	v_lshlrev_b32_e32 v246, 7, v18
	v_lshlrev_b32_e32 v247, 7, v19
	v_lshlrev_b32_e32 v248, 7, v20
	v_lshlrev_b32_e32 v249, 7, v221
	v_lshlrev_b32_e32 v250, 7, v222
	v_lshlrev_b32_e32 v251, 7, v223
	v_lshlrev_b32_e32 v252, 7, v224
	v_lshlrev_b32_e32 v253, 7, v225
	v_lshlrev_b32_e32 v254, 7, v226
	v_lshlrev_b32_e32 v213, 7, v1
	v_lshlrev_b32_e32 v214, 7, v5
	v_lshlrev_b32_e32 v215, 7, v7
	v_lshlrev_b32_e32 v216, 7, v9
	s_add_i32 s0, 0, 0x23f40
	s_movk_i32 s1, 0x3ff
	s_mov_b32 s49, 0x42fc0000
	v_lshlrev_b32_e32 v188, 1, v0
	v_lshlrev_b32_e32 v190, 1, v2
	s_mov_b64 s[12:13], 0x20000
	v_lshlrev_b32_e32 v217, 1, v4
	s_mov_b32 s15, 0x40400000
	s_mov_b32 s17, 0x41100000
	s_mov_b32 s25, 0x41300000
	s_mov_b32 s27, 0x41880000
	s_mov_b32 s29, 0x41980000
	s_mov_b32 s31, 0x41c80000
	s_mov_b32 s35, 0x41d80000
	s_mov_b64 s[50:51], 0x40000
	s_mov_b64 s[52:53], 0x60000
	s_mov_b64 s[54:55], 0xa0000
	s_mov_b32 s57, -1
	s_mov_b64 s[58:59], 0x80000
	s_mov_b32 s77, 0x5b200000
	v_lshlrev_b32_e32 v192, 1, v6
	v_lshlrev_b32_e32 v194, 1, v8
	v_lshlrev_b32_e32 v196, 1, v10
	v_lshlrev_b32_e32 v198, 1, v12
	v_lshlrev_b32_e32 v200, 1, v14
	v_mov_b32_e32 v218, 0x42800000
	v_mov_b32_e32 v219, 0xff800000
	v_readlane_b32 s94, v255, 8
	s_nop 0
	s_and_b32 s94, s94, 7
	s_mov_b32 s95, 0
	s_branch .LBB0_1939

.LBB0_1939:
	v_cndmask_b32_e64 v0, 0, 1, s[8:9]
	v_cmp_ne_u32_e64 s[2:3], 1, v0
	s_andn2_b64 vcc, exec, s[8:9]
	s_waitcnt lgkmcnt(0)
	s_barrier
	s_cbranch_vccnz .LBB0_1945
	v_mbcnt_lo_u32_b32 v0, -1, 0
	v_mbcnt_hi_u32_b32 v0, -1, v0
	s_nop 0
	v_cmp_eq_u32_e32 vcc, 0, v0
	s_and_saveexec_b64 s[6:7], vcc
	s_cbranch_execz .LBB0_1944
	s_mov_b64 s[44:45], exec
	v_mbcnt_lo_u32_b32 v0, s44, 0
	v_mbcnt_hi_u32_b32 v0, s45, v0
	v_cmp_eq_u32_e32 vcc, 0, v0
	s_and_saveexec_b64 s[40:41], vcc
	s_cbranch_execz .LBB0_1943
	v_readlane_b32 s42, v255, 4
	v_readlane_b32 s43, v255, 5
	s_cmp_lg_u32 s95, 0
	s_cbranch_scc1 .Lfq_steal
	s_lshl_b32 s10, s94, 8
	s_add_u32 s92, s42, s10
	s_addc_u32 s93, s43, 0
	v_mov_b32_e32 v1, 1
	s_mov_b32 s97, s94
	s_nop 1
	global_atomic_add v1, v189, v1, s[92:93] offset:512 sc0
	s_waitcnt vmcnt(0)
	v_readfirstlane_b32 s10, v1
	s_cmpk_lt_u32 s10, 0x80
	s_cbranch_scc1 .Lfq_got
	s_mov_b32 s95, 1
.Lfq_steal:
	s_mov_b64 exec, 0xff
	v_mbcnt_lo_u32_b32 v1, -1, 0
	v_lshlrev_b32_e32 v1, 8, v1
	s_nop 4
	global_load_dword v1, v1, s[42:43] offset:512 sc1
	s_waitcnt vmcnt(0)
	v_cmp_gt_u32_e32 vcc, 0x80, v1
	s_mov_b64 exec, 1
	s_cmp_eq_u64 vcc, 0
	s_cbranch_scc1 .Lfq_none
	s_ff1_i32_b64 s97, vcc
	s_lshl_b32 s10, s97, 8
	s_add_u32 s92, s42, s10
	s_addc_u32 s93, s43, 0
	v_mov_b32_e32 v1, 1
	s_nop 1
	global_atomic_add v1, v189, v1, s[92:93] offset:512 sc0
	s_waitcnt vmcnt(0)
	v_readfirstlane_b32 s10, v1
	s_cmpk_lt_u32 s10, 0x80
	s_cbranch_scc0 .Lfq_steal
.Lfq_got:
	s_lshr_b32 s92, s10, 4
	s_lshl_b32 s92, s92, 7
	s_bfe_u32 s93, s10, 0x20002
	s_lshl_b32 s97, s97, 2
	s_add_i32 s93, s93, s97
	s_lshl_b32 s93, s93, 2
	s_and_b32 s10, s10, 3
	s_or_b32 s10, s10, s93
	s_or_b32 s10, s10, s92
	s_branch .Lfq_done
.Lfq_none:
	s_movk_i32 s10, 0x400
.Lfq_done:
.LBB0_1943:
	s_or_b64 exec, exec, s[40:41]
	v_mov_b32_e32 v1, s0
	s_nop 0
	v_add_u32_e32 v0, s10, v0
	ds_write_b32 v1, v0
